# speedup vs baseline: 1.0020x; 1.0020x over previous
; #define p_rstd0 W_(float, OFF_RSTD0)
; __global__ void __launch_bounds__(512) fwd_megakernel(Params p) {
;     ...
;         #pragma unroll
;         for (int r = 0; r < 2; ++r) {
;           int row = row0 + r, b = row / LTOK, pos = row - b * LTOK;
;           src[r] = pos < NMETA ? p.meta + (long)pos * DM : xrow_ptr(p, b * SEQ + pos - NMETA);
;           #pragma unroll
;           for (int i = 0; i < 4; ++i) v[r][i] = *reinterpret_cast<const f32x4*>(src[r] + i * 256 + lane * 4);
;         }
;         #pragma unroll
;         for (int r = 0; r < 2; ++r) {
;           int row = row0 + r; float ss = 0.f;
;           #pragma unroll
;           for (int i = 0; i < 4; ++i) {
;             f32x4 t = v[r][i];
;             ss += t[0] * t[0] + t[1] * t[1] + t[2] * t[2] + t[3] * t[3];
;             u32x2 w = {cvtpk(t[0], t[1]), cvtpk(t[2], t[3])};
;             *reinterpret_cast<u32x2*>(p_xb + (long)row * DM + i * 256 + lane * 4) = w;
;           }
;           #pragma unroll
;           for (int s = 32; s >= 1; s >>= 1) ss += __shfl_xor(ss, s);
;           if (lane == 0) p_rstd0[row] = rsqrtf(ss * (1.f / DM) + EPS);
;         }
.LBB0_42:
	s_andn2_saveexec_b64 s[74:75], s[74:75]
	v_ashrrev_i32_e32 v1, 31, v0
	s_or_b64 exec, exec, s[74:75]
	v_lshlrev_b64 v[0:1], 12, v[0:1]
	v_lshl_add_u64 v[0:1], v[2:3], 0, v[0:1]
	v_lshl_add_u64 v[0:1], v[0:1], 0, v[42:43]
	global_load_dwordx4 v[12:15], v[0:1], off
	global_load_dwordx4 v[8:11], v[0:1], off offset:1024
	s_waitcnt lgkmcnt(0)
	global_load_dwordx4 v[4:7], v[0:1], off offset:2048
	s_nop 0
	global_load_dwordx4 v[0:3], v[0:1], off offset:3072
	s_waitcnt vmcnt(7)
	v_mul_f32_e32 v46, v29, v29
	s_waitcnt vmcnt(6)
	v_mul_f32_e32 v47, v25, v25
	v_fmac_f32_e32 v46, v28, v28
	v_fmac_f32_e32 v47, v24, v24
	v_fmac_f32_e32 v46, v30, v30
	v_fmac_f32_e32 v47, v26, v26
	v_fmac_f32_e32 v46, v31, v31
	v_fmac_f32_e32 v47, v27, v27
	v_add_f32_e32 v46, v46, v47
	s_waitcnt vmcnt(5)
	v_mul_f32_e32 v47, v21, v21
	v_fmac_f32_e32 v47, v20, v20
	v_fmac_f32_e32 v47, v22, v22
	v_fmac_f32_e32 v47, v23, v23
	v_add_f32_e32 v46, v46, v47
	s_waitcnt vmcnt(4)
	v_mul_f32_e32 v47, v17, v17
	v_fmac_f32_e32 v47, v16, v16
	v_fmac_f32_e32 v47, v18, v18
	v_fmac_f32_e32 v47, v19, v19
	v_add_f32_e32 v47, v46, v47
	v_and_b32_e32 v46, 64, v44
	v_add_u32_e32 v49, 64, v46
	v_xor_b32_e32 v46, 32, v44
	v_cmp_lt_i32_e32 vcc, v46, v49
	v_cvt_pk_bf16_f32 v52, v28, v29
	v_xor_b32_e32 v28, 4, v44
	v_cvt_pk_bf16_f32 v53, v30, v31
	s_nop 0
	v_cndmask_b32_e32 v46, v44, v46, vcc
	v_lshlrev_b32_e32 v46, 2, v46
	s_nop 1
	v_add_f32_dpp v47, v47, v47 quad_perm:[1,0,3,2] row_mask:0xf bank_mask:0xf
	s_nop 1
	v_add_f32_dpp v47, v47, v47 quad_perm:[2,3,0,1] row_mask:0xf bank_mask:0xf
	s_nop 1
	v_add_f32_dpp v47, v47, v47 row_half_mirror row_mask:0xf bank_mask:0xf
	s_nop 1
	v_add_f32_dpp v47, v47, v47 row_mirror row_mask:0xf bank_mask:0xf
	v_mov_b32_e32 v48, v47
	s_nop 1
	v_permlane16_swap_b32_e32 v47, v48
	v_add_f32_e32 v47, v47, v48
	v_mov_b32_e32 v48, v47
	s_nop 1
	v_permlane32_swap_b32_e32 v47, v48
	v_add_f32_e32 v47, v47, v48
	s_waitcnt lgkmcnt(0)
	v_mov_b32_e32 v48, v47
	v_xor_b32_e32 v47, 16, v44
	v_cmp_lt_i32_e32 vcc, v47, v49
	s_nop 1
	v_cndmask_b32_e32 v47, v44, v47, vcc
	v_lshlrev_b32_e32 v47, 2, v47
	s_waitcnt lgkmcnt(0)
	v_mov_b32_e32 v54, v48
	v_xor_b32_e32 v48, 8, v44
	v_cmp_lt_i32_e32 vcc, v48, v49
	v_lshl_add_u64 v[50:51], s[34:35], 0, v[36:37]
	s_nop 0
	v_cndmask_b32_e32 v48, v44, v48, vcc
	v_lshlrev_b32_e32 v48, 2, v48
	v_cmp_lt_i32_e32 vcc, v28, v49
	s_waitcnt lgkmcnt(0)
	v_mov_b32_e32 v29, v54
	v_cndmask_b32_e32 v28, v44, v28, vcc
	v_lshlrev_b32_e32 v28, 2, v28
	v_add_co_u32_e32 v30, vcc, s12, v50
	s_nop 1
	v_addc_co_u32_e32 v31, vcc, 0, v51, vcc
	global_store_dwordx2 v[30:31], v[52:53], off
	v_cvt_pk_bf16_f32 v50, v24, v25
	v_xor_b32_e32 v24, 2, v44
	v_cmp_lt_i32_e32 vcc, v24, v49
	s_waitcnt lgkmcnt(0)
	v_mov_b32_e32 v25, v29
	v_cvt_pk_bf16_f32 v51, v26, v27
	global_store_dwordx2 v[30:31], v[50:51], off offset:512
	v_cndmask_b32_e32 v24, v44, v24, vcc
	v_lshlrev_b32_e32 v24, 2, v24
	v_cvt_pk_bf16_f32 v26, v20, v21
	v_xor_b32_e32 v20, 1, v44
	v_cmp_lt_i32_e32 vcc, v20, v49
	v_cvt_pk_bf16_f32 v27, v22, v23
	s_waitcnt lgkmcnt(0)
	v_mov_b32_e32 v21, v25
	global_store_dwordx2 v[30:31], v[26:27], off offset:1024
	v_cndmask_b32_e32 v20, v44, v20, vcc
	v_lshlrev_b32_e32 v20, 2, v20
	v_cvt_pk_bf16_f32 v16, v16, v17
	v_cvt_pk_bf16_f32 v17, v18, v19
	global_store_dwordx2 v[30:31], v[16:17], off offset:1536
	s_and_saveexec_b64 s[74:75], s[0:1]
	s_cbranch_execz .LBB0_46
	s_waitcnt lgkmcnt(0)
	v_mov_b32_e32 v16, v21
	v_fmamk_f32 v16, v16, 0x3a800000, v45
	v_mul_f32_e32 v17, 0x4b800000, v16
	v_cmp_gt_f32_e32 vcc, s13, v16
	s_nop 1
	v_cndmask_b32_e32 v16, v16, v17, vcc
	v_rsq_f32_e32 v16, v16
	s_nop 0
	v_mul_f32_e32 v17, 0x45800000, v16
	v_cndmask_b32_e32 v18, v16, v17, vcc
	v_lshl_add_u64 v[16:17], s[34:35], 0, v[34:35]
	global_store_dword v[16:17], v18, off
.LBB0_46:
	s_or_b64 exec, exec, s[74:75]
	s_waitcnt vmcnt(7)
	v_mul_f32_e32 v16, v13, v13
	s_waitcnt vmcnt(6)
	v_mul_f32_e32 v17, v9, v9
	v_fmac_f32_e32 v16, v12, v12
	v_fmac_f32_e32 v17, v8, v8
	v_fmac_f32_e32 v16, v14, v14
	v_fmac_f32_e32 v17, v10, v10
	v_fmac_f32_e32 v16, v15, v15
	v_fmac_f32_e32 v17, v11, v11
	v_add_f32_e32 v16, v16, v17
	s_waitcnt vmcnt(5)
	v_mul_f32_e32 v17, v5, v5
	v_fmac_f32_e32 v17, v4, v4
	v_fmac_f32_e32 v17, v6, v6
	v_fmac_f32_e32 v17, v7, v7
	v_add_f32_e32 v16, v16, v17
	s_waitcnt vmcnt(4)
	v_mul_f32_e32 v17, v1, v1
	v_fmac_f32_e32 v17, v0, v0
	v_fmac_f32_e32 v17, v2, v2
	v_fmac_f32_e32 v17, v3, v3
	v_add_f32_e32 v16, v16, v17
	s_nop 1
	v_add_f32_dpp v16, v16, v16 quad_perm:[1,0,3,2] row_mask:0xf bank_mask:0xf
	s_nop 1
	v_add_f32_dpp v16, v16, v16 quad_perm:[2,3,0,1] row_mask:0xf bank_mask:0xf
	s_nop 1
	v_add_f32_dpp v16, v16, v16 row_half_mirror row_mask:0xf bank_mask:0xf
	s_nop 1
	v_add_f32_dpp v16, v16, v16 row_mirror row_mask:0xf bank_mask:0xf
	v_mov_b32_e32 v17, v16
	s_nop 1
	v_permlane16_swap_b32_e32 v16, v17
	v_add_f32_e32 v16, v16, v17
	v_mov_b32_e32 v17, v16
	s_nop 1
	v_permlane32_swap_b32_e32 v16, v17
	v_add_f32_e32 v16, v16, v17
	v_cvt_pk_bf16_f32 v12, v12, v13
	v_cvt_pk_bf16_f32 v13, v14, v15
	s_waitcnt lgkmcnt(0)
	v_mov_b32_e32 v18, v16
	v_lshl_add_u64 v[16:17], s[34:35], 0, v[40:41]
	v_add_co_u32_e32 v14, vcc, 0x21000000, v16
	s_waitcnt lgkmcnt(0)
	v_addc_co_u32_e32 v15, vcc, 0, v17, vcc
	global_store_dwordx2 v[14:15], v[12:13], off offset:2048
	v_cvt_pk_bf16_f32 v8, v8, v9
	s_waitcnt lgkmcnt(0)
	v_mov_b32_e32 v16, v18
	v_cvt_pk_bf16_f32 v9, v10, v11
	global_store_dwordx2 v[14:15], v[8:9], off offset:2560
	v_cvt_pk_bf16_f32 v8, v4, v5
	v_cvt_pk_bf16_f32 v9, v6, v7
	s_waitcnt lgkmcnt(0)
	v_mov_b32_e32 v12, v16
	global_store_dwordx2 v[14:15], v[8:9], off offset:3072
	v_cvt_pk_bf16_f32 v0, v0, v1
	v_cvt_pk_bf16_f32 v1, v2, v3
	global_store_dwordx2 v[14:15], v[0:1], off offset:3584
	s_waitcnt lgkmcnt(0)
	v_mov_b32_e32 v4, v12
	s_and_saveexec_b64 s[74:75], s[0:1]
	s_cbranch_execz .LBB0_35
	s_waitcnt lgkmcnt(0)
	v_mov_b32_e32 v0, v4
	v_fmamk_f32 v0, v0, 0x3a800000, v45
	v_mul_f32_e32 v1, 0x4b800000, v0
	v_cmp_gt_f32_e32 vcc, s13, v0
	s_nop 1
	v_cndmask_b32_e32 v0, v0, v1, vcc
	v_rsq_f32_e32 v0, v0
	s_nop 0
	v_mul_f32_e32 v1, 0x45800000, v0
	v_cndmask_b32_e32 v2, v0, v1, vcc
	v_lshl_add_u64 v[0:1], s[34:35], 0, v[38:39]
	global_store_dword v[0:1], v2, off
	s_branch .LBB0_35
